# s_setprio strategy step (a): one static priority raise for the later-dispatched half (blocks 256..511) at the start of the GEMM phases, flips deleted
# baseline (speedup 1.0000x reference)
.LBB0_123:
	s_cmp_ge_u32 s2, 0x100
	s_cbranch_scc0 .Lprio_skip0
	s_setprio 1
